# conversion item head: counted waits (guide 7.2) - the column absmax folds each group of 4 row loads as it lands instead of waiting for all 32
# baseline (speedup 1.0000x reference)
.Lc16_gates_loop:
	s_lshl_b32 s2, s0, 4
	s_mov_b32 s60, s2
	s_lshl_b32 s63, s11, 9
	s_add_u32 s63, s63, 0x21000
	s_lshl_b32 s3, s1, 6
	s_add_u32 s3, s3, s63
	v_add_u32_e32 v172, s3, v230
	v_add_u32_e32 v173, s63, v230
	s_waitcnt vmcnt(28)
	v_max3_f32 v216, |v6|, |v10|, |v14|
	v_max_f32_e64 v216, v216, |v18|
	v_max3_f32 v217, |v7|, |v11|, |v15|
	v_max_f32_e64 v217, v217, |v19|
	v_max3_f32 v218, |v8|, |v12|, |v16|
	v_max_f32_e64 v218, v218, |v20|
	v_max3_f32 v219, |v9|, |v13|, |v17|
	v_max_f32_e64 v219, v219, |v21|
	s_waitcnt vmcnt(24)
	v_max3_f32 v216, v216, |v22|, |v26|
	v_max3_f32 v216, v216, |v30|, |v34|
	v_max3_f32 v217, v217, |v23|, |v27|
	v_max3_f32 v217, v217, |v31|, |v35|
	v_max3_f32 v218, v218, |v24|, |v28|
	v_max3_f32 v218, v218, |v32|, |v36|
	v_max3_f32 v219, v219, |v25|, |v29|
	v_max3_f32 v219, v219, |v33|, |v37|
	s_waitcnt vmcnt(20)
	v_max3_f32 v216, v216, |v38|, |v42|
	v_max3_f32 v216, v216, |v46|, |v50|
	v_max3_f32 v217, v217, |v39|, |v43|
	v_max3_f32 v217, v217, |v47|, |v51|
	v_max3_f32 v218, v218, |v40|, |v44|
	v_max3_f32 v218, v218, |v48|, |v52|
	v_max3_f32 v219, v219, |v41|, |v45|
	v_max3_f32 v219, v219, |v49|, |v53|
	s_waitcnt vmcnt(16)
	v_max3_f32 v216, v216, |v54|, |v58|
	v_max3_f32 v216, v216, |v62|, |v66|
	v_max3_f32 v217, v217, |v55|, |v59|
	v_max3_f32 v217, v217, |v63|, |v67|
	v_max3_f32 v218, v218, |v56|, |v60|
	v_max3_f32 v218, v218, |v64|, |v68|
	v_max3_f32 v219, v219, |v57|, |v61|
	v_max3_f32 v219, v219, |v65|, |v69|
	s_waitcnt vmcnt(12)
	v_max3_f32 v216, v216, |v70|, |v74|
	v_max3_f32 v216, v216, |v78|, |v82|
	v_max3_f32 v217, v217, |v71|, |v75|
	v_max3_f32 v217, v217, |v79|, |v83|
	v_max3_f32 v218, v218, |v72|, |v76|
	v_max3_f32 v218, v218, |v80|, |v84|
	v_max3_f32 v219, v219, |v73|, |v77|
	v_max3_f32 v219, v219, |v81|, |v85|
	s_waitcnt vmcnt(8)
	v_max3_f32 v216, v216, |v86|, |v90|
	v_max3_f32 v216, v216, |v94|, |v98|
	v_max3_f32 v217, v217, |v87|, |v91|
	v_max3_f32 v217, v217, |v95|, |v99|
	v_max3_f32 v218, v218, |v88|, |v92|
	v_max3_f32 v218, v218, |v96|, |v100|
	v_max3_f32 v219, v219, |v89|, |v93|
	v_max3_f32 v219, v219, |v97|, |v101|
	s_waitcnt vmcnt(4)
	v_max3_f32 v216, v216, |v102|, |v106|
	v_max3_f32 v216, v216, |v110|, |v114|
	v_max3_f32 v217, v217, |v103|, |v107|
	v_max3_f32 v217, v217, |v111|, |v115|
	v_max3_f32 v218, v218, |v104|, |v108|
	v_max3_f32 v218, v218, |v112|, |v116|
	v_max3_f32 v219, v219, |v105|, |v109|
	v_max3_f32 v219, v219, |v113|, |v117|
	s_waitcnt vmcnt(0)
	v_max3_f32 v216, v216, |v118|, |v122|
	v_max3_f32 v216, v216, |v126|, |v130|
	v_max3_f32 v217, v217, |v119|, |v123|
	v_max3_f32 v217, v217, |v127|, |v131|
	v_max3_f32 v218, v218, |v120|, |v124|
	v_max3_f32 v218, v218, |v128|, |v132|
	v_max3_f32 v219, v219, |v121|, |v125|
	v_max3_f32 v219, v219, |v129|, |v133|
	s_nop 0
	ds_bpermute_b32 v174, v192, v216
	ds_bpermute_b32 v175, v192, v217
	ds_bpermute_b32 v176, v192, v218
	ds_bpermute_b32 v177, v192, v219
	s_waitcnt lgkmcnt(0)
	v_max_f32_e32 v216, v216, v174
	v_max_f32_e32 v217, v217, v175
	v_max_f32_e32 v218, v218, v176
	v_max_f32_e32 v219, v219, v177
	ds_bpermute_b32 v174, v193, v216
	ds_bpermute_b32 v175, v193, v217
	ds_bpermute_b32 v176, v193, v218
	ds_bpermute_b32 v177, v193, v219
	s_waitcnt lgkmcnt(0)
	v_max_f32_e32 v216, v216, v174
	v_max_f32_e32 v217, v217, v175
	v_max_f32_e32 v218, v218, v176
	v_max_f32_e32 v219, v219, v177
	ds_bpermute_b32 v174, v194, v216
	ds_bpermute_b32 v175, v194, v217
	ds_bpermute_b32 v176, v194, v218
	ds_bpermute_b32 v177, v194, v219
	s_waitcnt lgkmcnt(0)
	v_max_f32_e32 v216, v216, v174
	v_max_f32_e32 v217, v217, v175
	v_max_f32_e32 v218, v218, v176
	v_max_f32_e32 v219, v219, v177
	ds_bpermute_b32 v174, v195, v216
	ds_bpermute_b32 v175, v195, v217
	ds_bpermute_b32 v176, v195, v218
	ds_bpermute_b32 v177, v195, v219
	s_waitcnt lgkmcnt(0)
	v_max_f32_e32 v216, v216, v174
	v_max_f32_e32 v217, v217, v175
	v_max_f32_e32 v218, v218, v176
	v_max_f32_e32 v219, v219, v177
	s_mov_b64 s[70:71], exec
	s_mov_b64 exec, 15
	ds_write_b128 v172, v[216:219]
	s_mov_b64 exec, s[70:71]
	s_waitcnt lgkmcnt(0)
	s_barrier
	ds_read_b128 v[140:143], v173 offset:0
	ds_read_b128 v[144:147], v173 offset:64
	ds_read_b128 v[148:151], v173 offset:128
	ds_read_b128 v[152:155], v173 offset:192
	ds_read_b128 v[156:159], v173 offset:256
	ds_read_b128 v[160:163], v173 offset:320
	ds_read_b128 v[164:167], v173 offset:384
	ds_read_b128 v[232:235], v173 offset:448
	s_waitcnt lgkmcnt(0)
	v_max3_f32 v220, v140, v144, v148
	v_max3_f32 v220, v220, v152, v156
	v_max3_f32 v220, v220, v160, v164
	v_max_f32_e32 v220, v220, v232
	v_max3_f32 v221, v141, v145, v149
	v_max3_f32 v221, v221, v153, v157
	v_max3_f32 v221, v221, v161, v165
	v_max_f32_e32 v221, v221, v233
	v_max3_f32 v222, v142, v146, v150
	v_max3_f32 v222, v222, v154, v158
	v_max3_f32 v222, v222, v162, v166
	v_max_f32_e32 v222, v222, v234
	v_max3_f32 v223, v143, v147, v151
	v_max3_f32 v223, v223, v155, v159
	v_max3_f32 v223, v223, v163, v167
	v_max_f32_e32 v223, v223, v235
	s_cmp_lg_u32 s1, 0
	s_cbranch_scc1 .Lc16_gates_nocm
	s_lshl_b32 s3, s2, 2
	s_add_u32 s56, s34, s3
	s_addc_u32 s57, s35, 0
	s_add_u32 s56, s56, 0x80000
	s_addc_u32 s57, s57, 0
	s_mov_b64 s[70:71], exec
	s_mov_b64 exec, 15
	global_store_dwordx4 v230, v[220:223], s[56:57]
	s_mov_b64 exec, s[70:71]

.Lc16_ffn1_loop:
	s_lshl_b32 s2, s0, 4
	s_cmp_ge_u32 s2, 0x2b00
	s_cselect_b32 s75, 128, 0
	s_cselect_b32 s3, 0x2b00, 0
	s_sub_u32 s3, s2, s3
	s_lshr_b32 s60, s3, 7
	s_lshl_b32 s60, s60, 8
	s_and_b32 s3, s3, 127
	s_add_u32 s60, s60, s3
	s_add_u32 s60, s60, s75
	s_lshl_b32 s63, s11, 9
	s_add_u32 s63, s63, 0x21000
	s_lshl_b32 s3, s1, 6
	s_add_u32 s3, s3, s63
	v_add_u32_e32 v172, s3, v230
	v_add_u32_e32 v173, s63, v230
	s_waitcnt vmcnt(28)
	v_max3_f32 v216, |v6|, |v10|, |v14|
	v_max_f32_e64 v216, v216, |v18|
	v_max3_f32 v217, |v7|, |v11|, |v15|
	v_max_f32_e64 v217, v217, |v19|
	v_max3_f32 v218, |v8|, |v12|, |v16|
	v_max_f32_e64 v218, v218, |v20|
	v_max3_f32 v219, |v9|, |v13|, |v17|
	v_max_f32_e64 v219, v219, |v21|
	s_waitcnt vmcnt(24)
	v_max3_f32 v216, v216, |v22|, |v26|
	v_max3_f32 v216, v216, |v30|, |v34|
	v_max3_f32 v217, v217, |v23|, |v27|
	v_max3_f32 v217, v217, |v31|, |v35|
	v_max3_f32 v218, v218, |v24|, |v28|
	v_max3_f32 v218, v218, |v32|, |v36|
	v_max3_f32 v219, v219, |v25|, |v29|
	v_max3_f32 v219, v219, |v33|, |v37|
	s_waitcnt vmcnt(20)
	v_max3_f32 v216, v216, |v38|, |v42|
	v_max3_f32 v216, v216, |v46|, |v50|
	v_max3_f32 v217, v217, |v39|, |v43|
	v_max3_f32 v217, v217, |v47|, |v51|
	v_max3_f32 v218, v218, |v40|, |v44|
	v_max3_f32 v218, v218, |v48|, |v52|
	v_max3_f32 v219, v219, |v41|, |v45|
	v_max3_f32 v219, v219, |v49|, |v53|
	s_waitcnt vmcnt(16)
	v_max3_f32 v216, v216, |v54|, |v58|
	v_max3_f32 v216, v216, |v62|, |v66|
	v_max3_f32 v217, v217, |v55|, |v59|
	v_max3_f32 v217, v217, |v63|, |v67|
	v_max3_f32 v218, v218, |v56|, |v60|
	v_max3_f32 v218, v218, |v64|, |v68|
	v_max3_f32 v219, v219, |v57|, |v61|
	v_max3_f32 v219, v219, |v65|, |v69|
	s_waitcnt vmcnt(12)
	v_max3_f32 v216, v216, |v70|, |v74|
	v_max3_f32 v216, v216, |v78|, |v82|
	v_max3_f32 v217, v217, |v71|, |v75|
	v_max3_f32 v217, v217, |v79|, |v83|
	v_max3_f32 v218, v218, |v72|, |v76|
	v_max3_f32 v218, v218, |v80|, |v84|
	v_max3_f32 v219, v219, |v73|, |v77|
	v_max3_f32 v219, v219, |v81|, |v85|
	s_waitcnt vmcnt(8)
	v_max3_f32 v216, v216, |v86|, |v90|
	v_max3_f32 v216, v216, |v94|, |v98|
	v_max3_f32 v217, v217, |v87|, |v91|
	v_max3_f32 v217, v217, |v95|, |v99|
	v_max3_f32 v218, v218, |v88|, |v92|
	v_max3_f32 v218, v218, |v96|, |v100|
	v_max3_f32 v219, v219, |v89|, |v93|
	v_max3_f32 v219, v219, |v97|, |v101|
	s_waitcnt vmcnt(4)
	v_max3_f32 v216, v216, |v102|, |v106|
	v_max3_f32 v216, v216, |v110|, |v114|
	v_max3_f32 v217, v217, |v103|, |v107|
	v_max3_f32 v217, v217, |v111|, |v115|
	v_max3_f32 v218, v218, |v104|, |v108|
	v_max3_f32 v218, v218, |v112|, |v116|
	v_max3_f32 v219, v219, |v105|, |v109|
	v_max3_f32 v219, v219, |v113|, |v117|
	s_waitcnt vmcnt(0)
	v_max3_f32 v216, v216, |v118|, |v122|
	v_max3_f32 v216, v216, |v126|, |v130|
	v_max3_f32 v217, v217, |v119|, |v123|
	v_max3_f32 v217, v217, |v127|, |v131|
	v_max3_f32 v218, v218, |v120|, |v124|
	v_max3_f32 v218, v218, |v128|, |v132|
	v_max3_f32 v219, v219, |v121|, |v125|
	v_max3_f32 v219, v219, |v129|, |v133|
	s_nop 0
	ds_bpermute_b32 v174, v192, v216
	ds_bpermute_b32 v175, v192, v217
	ds_bpermute_b32 v176, v192, v218
	ds_bpermute_b32 v177, v192, v219
	s_waitcnt lgkmcnt(0)
	v_max_f32_e32 v216, v216, v174
	v_max_f32_e32 v217, v217, v175
	v_max_f32_e32 v218, v218, v176
	v_max_f32_e32 v219, v219, v177
	ds_bpermute_b32 v174, v193, v216
	ds_bpermute_b32 v175, v193, v217
	ds_bpermute_b32 v176, v193, v218
	ds_bpermute_b32 v177, v193, v219
	s_waitcnt lgkmcnt(0)
	v_max_f32_e32 v216, v216, v174
	v_max_f32_e32 v217, v217, v175
	v_max_f32_e32 v218, v218, v176
	v_max_f32_e32 v219, v219, v177
	ds_bpermute_b32 v174, v194, v216
	ds_bpermute_b32 v175, v194, v217
	ds_bpermute_b32 v176, v194, v218
	ds_bpermute_b32 v177, v194, v219
	s_waitcnt lgkmcnt(0)
	v_max_f32_e32 v216, v216, v174
	v_max_f32_e32 v217, v217, v175
	v_max_f32_e32 v218, v218, v176
	v_max_f32_e32 v219, v219, v177
	ds_bpermute_b32 v174, v195, v216
	ds_bpermute_b32 v175, v195, v217
	ds_bpermute_b32 v176, v195, v218
	ds_bpermute_b32 v177, v195, v219
	s_waitcnt lgkmcnt(0)
	v_max_f32_e32 v216, v216, v174
	v_max_f32_e32 v217, v217, v175
	v_max_f32_e32 v218, v218, v176
	v_max_f32_e32 v219, v219, v177
	s_mov_b64 s[70:71], exec
	s_mov_b64 exec, 15
	ds_write_b128 v172, v[216:219]
	s_mov_b64 exec, s[70:71]
	s_waitcnt lgkmcnt(0)
	s_barrier
	ds_read_b128 v[140:143], v173 offset:0
	ds_read_b128 v[144:147], v173 offset:64
	ds_read_b128 v[148:151], v173 offset:128
	ds_read_b128 v[152:155], v173 offset:192
	ds_read_b128 v[156:159], v173 offset:256
	ds_read_b128 v[160:163], v173 offset:320
	ds_read_b128 v[164:167], v173 offset:384
	ds_read_b128 v[232:235], v173 offset:448
	s_waitcnt lgkmcnt(0)
	v_max3_f32 v220, v140, v144, v148
	v_max3_f32 v220, v220, v152, v156
	v_max3_f32 v220, v220, v160, v164
	v_max_f32_e32 v220, v220, v232
	v_max3_f32 v221, v141, v145, v149
	v_max3_f32 v221, v221, v153, v157
	v_max3_f32 v221, v221, v161, v165
	v_max_f32_e32 v221, v221, v233
	v_max3_f32 v222, v142, v146, v150
	v_max3_f32 v222, v222, v154, v158
	v_max3_f32 v222, v222, v162, v166
	v_max_f32_e32 v222, v222, v234
	v_max3_f32 v223, v143, v147, v151
	v_max3_f32 v223, v223, v155, v159
	v_max3_f32 v223, v223, v163, v167
	v_max_f32_e32 v223, v223, v235
	s_cmp_lg_u32 s1, 0
	s_cbranch_scc1 .Lc16_ffn1_nocm
	s_lshl_b32 s3, s2, 2
	s_add_u32 s56, s34, s3
	s_addc_u32 s57, s35, 0
	s_add_u32 s56, s56, 0x40000
	s_addc_u32 s57, s57, 0
	s_mov_b64 s[70:71], exec
	s_mov_b64 exec, 15
	global_store_dwordx4 v230, v[220:223], s[56:57]
	s_mov_b64 exec, s[70:71]

.Lc16_mixer_loop:
	s_lshl_b32 s2, s0, 4
	s_mov_b32 s60, s2
	s_lshl_b32 s63, s11, 9
	s_add_u32 s63, s63, 0x21000
	s_lshl_b32 s3, s1, 6
	s_add_u32 s3, s3, s63
	v_add_u32_e32 v172, s3, v230
	v_add_u32_e32 v173, s63, v230
	s_waitcnt vmcnt(28)
	v_max3_f32 v216, |v6|, |v10|, |v14|
	v_max_f32_e64 v216, v216, |v18|
	v_max3_f32 v217, |v7|, |v11|, |v15|
	v_max_f32_e64 v217, v217, |v19|
	v_max3_f32 v218, |v8|, |v12|, |v16|
	v_max_f32_e64 v218, v218, |v20|
	v_max3_f32 v219, |v9|, |v13|, |v17|
	v_max_f32_e64 v219, v219, |v21|
	s_waitcnt vmcnt(24)
	v_max3_f32 v216, v216, |v22|, |v26|
	v_max3_f32 v216, v216, |v30|, |v34|
	v_max3_f32 v217, v217, |v23|, |v27|
	v_max3_f32 v217, v217, |v31|, |v35|
	v_max3_f32 v218, v218, |v24|, |v28|
	v_max3_f32 v218, v218, |v32|, |v36|
	v_max3_f32 v219, v219, |v25|, |v29|
	v_max3_f32 v219, v219, |v33|, |v37|
	s_waitcnt vmcnt(20)
	v_max3_f32 v216, v216, |v38|, |v42|
	v_max3_f32 v216, v216, |v46|, |v50|
	v_max3_f32 v217, v217, |v39|, |v43|
	v_max3_f32 v217, v217, |v47|, |v51|
	v_max3_f32 v218, v218, |v40|, |v44|
	v_max3_f32 v218, v218, |v48|, |v52|
	v_max3_f32 v219, v219, |v41|, |v45|
	v_max3_f32 v219, v219, |v49|, |v53|
	s_waitcnt vmcnt(16)
	v_max3_f32 v216, v216, |v54|, |v58|
	v_max3_f32 v216, v216, |v62|, |v66|
	v_max3_f32 v217, v217, |v55|, |v59|
	v_max3_f32 v217, v217, |v63|, |v67|
	v_max3_f32 v218, v218, |v56|, |v60|
	v_max3_f32 v218, v218, |v64|, |v68|
	v_max3_f32 v219, v219, |v57|, |v61|
	v_max3_f32 v219, v219, |v65|, |v69|
	s_waitcnt vmcnt(12)
	v_max3_f32 v216, v216, |v70|, |v74|
	v_max3_f32 v216, v216, |v78|, |v82|
	v_max3_f32 v217, v217, |v71|, |v75|
	v_max3_f32 v217, v217, |v79|, |v83|
	v_max3_f32 v218, v218, |v72|, |v76|
	v_max3_f32 v218, v218, |v80|, |v84|
	v_max3_f32 v219, v219, |v73|, |v77|
	v_max3_f32 v219, v219, |v81|, |v85|
	s_waitcnt vmcnt(8)
	v_max3_f32 v216, v216, |v86|, |v90|
	v_max3_f32 v216, v216, |v94|, |v98|
	v_max3_f32 v217, v217, |v87|, |v91|
	v_max3_f32 v217, v217, |v95|, |v99|
	v_max3_f32 v218, v218, |v88|, |v92|
	v_max3_f32 v218, v218, |v96|, |v100|
	v_max3_f32 v219, v219, |v89|, |v93|
	v_max3_f32 v219, v219, |v97|, |v101|
	s_waitcnt vmcnt(4)
	v_max3_f32 v216, v216, |v102|, |v106|
	v_max3_f32 v216, v216, |v110|, |v114|
	v_max3_f32 v217, v217, |v103|, |v107|
	v_max3_f32 v217, v217, |v111|, |v115|
	v_max3_f32 v218, v218, |v104|, |v108|
	v_max3_f32 v218, v218, |v112|, |v116|
	v_max3_f32 v219, v219, |v105|, |v109|
	v_max3_f32 v219, v219, |v113|, |v117|
	s_waitcnt vmcnt(0)
	v_max3_f32 v216, v216, |v118|, |v122|
	v_max3_f32 v216, v216, |v126|, |v130|
	v_max3_f32 v217, v217, |v119|, |v123|
	v_max3_f32 v217, v217, |v127|, |v131|
	v_max3_f32 v218, v218, |v120|, |v124|
	v_max3_f32 v218, v218, |v128|, |v132|
	v_max3_f32 v219, v219, |v121|, |v125|
	v_max3_f32 v219, v219, |v129|, |v133|
	s_nop 0
	ds_bpermute_b32 v174, v192, v216
	ds_bpermute_b32 v175, v192, v217
	ds_bpermute_b32 v176, v192, v218
	ds_bpermute_b32 v177, v192, v219
	s_waitcnt lgkmcnt(0)
	v_max_f32_e32 v216, v216, v174
	v_max_f32_e32 v217, v217, v175
	v_max_f32_e32 v218, v218, v176
	v_max_f32_e32 v219, v219, v177
	ds_bpermute_b32 v174, v193, v216
	ds_bpermute_b32 v175, v193, v217
	ds_bpermute_b32 v176, v193, v218
	ds_bpermute_b32 v177, v193, v219
	s_waitcnt lgkmcnt(0)
	v_max_f32_e32 v216, v216, v174
	v_max_f32_e32 v217, v217, v175
	v_max_f32_e32 v218, v218, v176
	v_max_f32_e32 v219, v219, v177
	ds_bpermute_b32 v174, v194, v216
	ds_bpermute_b32 v175, v194, v217
	ds_bpermute_b32 v176, v194, v218
	ds_bpermute_b32 v177, v194, v219
	s_waitcnt lgkmcnt(0)
	v_max_f32_e32 v216, v216, v174
	v_max_f32_e32 v217, v217, v175
	v_max_f32_e32 v218, v218, v176
	v_max_f32_e32 v219, v219, v177
	ds_bpermute_b32 v174, v195, v216
	ds_bpermute_b32 v175, v195, v217
	ds_bpermute_b32 v176, v195, v218
	ds_bpermute_b32 v177, v195, v219
	s_waitcnt lgkmcnt(0)
	v_max_f32_e32 v216, v216, v174
	v_max_f32_e32 v217, v217, v175
	v_max_f32_e32 v218, v218, v176
	v_max_f32_e32 v219, v219, v177
	s_mov_b64 s[70:71], exec
	s_mov_b64 exec, 15
	ds_write_b128 v172, v[216:219]
	s_mov_b64 exec, s[70:71]
	s_waitcnt lgkmcnt(0)
	s_barrier
	ds_read_b128 v[140:143], v173 offset:0
	ds_read_b128 v[144:147], v173 offset:64
	ds_read_b128 v[148:151], v173 offset:128
	ds_read_b128 v[152:155], v173 offset:192
	ds_read_b128 v[156:159], v173 offset:256
	ds_read_b128 v[160:163], v173 offset:320
	ds_read_b128 v[164:167], v173 offset:384
	ds_read_b128 v[232:235], v173 offset:448
	s_waitcnt lgkmcnt(0)
	v_max3_f32 v220, v140, v144, v148
	v_max3_f32 v220, v220, v152, v156
	v_max3_f32 v220, v220, v160, v164
	v_max_f32_e32 v220, v220, v232
	v_max3_f32 v221, v141, v145, v149
	v_max3_f32 v221, v221, v153, v157
	v_max3_f32 v221, v221, v161, v165
	v_max_f32_e32 v221, v221, v233
	v_max3_f32 v222, v142, v146, v150
	v_max3_f32 v222, v222, v154, v158
	v_max3_f32 v222, v222, v162, v166
	v_max_f32_e32 v222, v222, v234
	v_max3_f32 v223, v143, v147, v151
	v_max3_f32 v223, v223, v155, v159
	v_max3_f32 v223, v223, v163, v167
	v_max_f32_e32 v223, v223, v235
	s_cmp_lg_u32 s1, 0
	s_cbranch_scc1 .Lc16_mixer_nocm
	s_lshl_b32 s3, s2, 2
	s_add_u32 s56, s34, s3
	s_addc_u32 s57, s35, 0
	s_add_u32 s56, s56, 0xe0000
	s_addc_u32 s57, s57, 0
	s_mov_b64 s[70:71], exec
	s_mov_b64 exec, 15
	global_store_dwordx4 v230, v[220:223], s[56:57]
	s_mov_b64 exec, s[70:71]

.Lc16p3_ffn2_loop:
	s_lshl_b32 s2, s0, 4
	s_cmp_ge_u32 s2, 0x2b00
	s_cselect_b32 s12, 128, 0
	s_cselect_b32 s3, 0x2b00, 0
	s_sub_u32 s3, s2, s3
	s_lshr_b32 s6, s3, 7
	s_lshl_b32 s6, s6, 8
	s_and_b32 s3, s3, 127
	s_add_u32 s6, s6, s3
	s_add_u32 s6, s6, s12
	s_lshl_b32 s10, s5, 9
	s_add_u32 s10, s10, 0x21000
	s_lshl_b32 s3, s1, 6
	s_add_u32 s3, s3, s10
	v_add_u32_e32 v172, s3, v230
	v_add_u32_e32 v173, s10, v230
	s_waitcnt vmcnt(28)
	v_max3_f32 v216, |v6|, |v10|, |v14|
	v_max_f32_e64 v216, v216, |v18|
	v_max3_f32 v217, |v7|, |v11|, |v15|
	v_max_f32_e64 v217, v217, |v19|
	v_max3_f32 v218, |v8|, |v12|, |v16|
	v_max_f32_e64 v218, v218, |v20|
	v_max3_f32 v219, |v9|, |v13|, |v17|
	v_max_f32_e64 v219, v219, |v21|
	s_waitcnt vmcnt(24)
	v_max3_f32 v216, v216, |v22|, |v26|
	v_max3_f32 v216, v216, |v30|, |v34|
	v_max3_f32 v217, v217, |v23|, |v27|
	v_max3_f32 v217, v217, |v31|, |v35|
	v_max3_f32 v218, v218, |v24|, |v28|
	v_max3_f32 v218, v218, |v32|, |v36|
	v_max3_f32 v219, v219, |v25|, |v29|
	v_max3_f32 v219, v219, |v33|, |v37|
	s_waitcnt vmcnt(20)
	v_max3_f32 v216, v216, |v38|, |v42|
	v_max3_f32 v216, v216, |v46|, |v50|
	v_max3_f32 v217, v217, |v39|, |v43|
	v_max3_f32 v217, v217, |v47|, |v51|
	v_max3_f32 v218, v218, |v40|, |v44|
	v_max3_f32 v218, v218, |v48|, |v52|
	v_max3_f32 v219, v219, |v41|, |v45|
	v_max3_f32 v219, v219, |v49|, |v53|
	s_waitcnt vmcnt(16)
	v_max3_f32 v216, v216, |v54|, |v58|
	v_max3_f32 v216, v216, |v62|, |v66|
	v_max3_f32 v217, v217, |v55|, |v59|
	v_max3_f32 v217, v217, |v63|, |v67|
	v_max3_f32 v218, v218, |v56|, |v60|
	v_max3_f32 v218, v218, |v64|, |v68|
	v_max3_f32 v219, v219, |v57|, |v61|
	v_max3_f32 v219, v219, |v65|, |v69|
	s_waitcnt vmcnt(12)
	v_max3_f32 v216, v216, |v70|, |v74|
	v_max3_f32 v216, v216, |v78|, |v82|
	v_max3_f32 v217, v217, |v71|, |v75|
	v_max3_f32 v217, v217, |v79|, |v83|
	v_max3_f32 v218, v218, |v72|, |v76|
	v_max3_f32 v218, v218, |v80|, |v84|
	v_max3_f32 v219, v219, |v73|, |v77|
	v_max3_f32 v219, v219, |v81|, |v85|
	s_waitcnt vmcnt(8)
	v_max3_f32 v216, v216, |v86|, |v90|
	v_max3_f32 v216, v216, |v94|, |v98|
	v_max3_f32 v217, v217, |v87|, |v91|
	v_max3_f32 v217, v217, |v95|, |v99|
	v_max3_f32 v218, v218, |v88|, |v92|
	v_max3_f32 v218, v218, |v96|, |v100|
	v_max3_f32 v219, v219, |v89|, |v93|
	v_max3_f32 v219, v219, |v97|, |v101|
	s_waitcnt vmcnt(4)
	v_max3_f32 v216, v216, |v102|, |v106|
	v_max3_f32 v216, v216, |v110|, |v114|
	v_max3_f32 v217, v217, |v103|, |v107|
	v_max3_f32 v217, v217, |v111|, |v115|
	v_max3_f32 v218, v218, |v104|, |v108|
	v_max3_f32 v218, v218, |v112|, |v116|
	v_max3_f32 v219, v219, |v105|, |v109|
	v_max3_f32 v219, v219, |v113|, |v117|
	s_waitcnt vmcnt(0)
	v_max3_f32 v216, v216, |v118|, |v122|
	v_max3_f32 v216, v216, |v126|, |v130|
	v_max3_f32 v217, v217, |v119|, |v123|
	v_max3_f32 v217, v217, |v127|, |v131|
	v_max3_f32 v218, v218, |v120|, |v124|
	v_max3_f32 v218, v218, |v128|, |v132|
	v_max3_f32 v219, v219, |v121|, |v125|
	v_max3_f32 v219, v219, |v129|, |v133|
	s_nop 0
	ds_bpermute_b32 v174, v192, v216
	ds_bpermute_b32 v175, v192, v217
	ds_bpermute_b32 v176, v192, v218
	ds_bpermute_b32 v177, v192, v219
	s_waitcnt lgkmcnt(0)
	v_max_f32_e32 v216, v216, v174
	v_max_f32_e32 v217, v217, v175
	v_max_f32_e32 v218, v218, v176
	v_max_f32_e32 v219, v219, v177
	ds_bpermute_b32 v174, v193, v216
	ds_bpermute_b32 v175, v193, v217
	ds_bpermute_b32 v176, v193, v218
	ds_bpermute_b32 v177, v193, v219
	s_waitcnt lgkmcnt(0)
	v_max_f32_e32 v216, v216, v174
	v_max_f32_e32 v217, v217, v175
	v_max_f32_e32 v218, v218, v176
	v_max_f32_e32 v219, v219, v177
	ds_bpermute_b32 v174, v194, v216
	ds_bpermute_b32 v175, v194, v217
	ds_bpermute_b32 v176, v194, v218
	ds_bpermute_b32 v177, v194, v219
	s_waitcnt lgkmcnt(0)
	v_max_f32_e32 v216, v216, v174
	v_max_f32_e32 v217, v217, v175
	v_max_f32_e32 v218, v218, v176
	v_max_f32_e32 v219, v219, v177
	ds_bpermute_b32 v174, v195, v216
	ds_bpermute_b32 v175, v195, v217
	ds_bpermute_b32 v176, v195, v218
	ds_bpermute_b32 v177, v195, v219
	s_waitcnt lgkmcnt(0)
	v_max_f32_e32 v216, v216, v174
	v_max_f32_e32 v217, v217, v175
	v_max_f32_e32 v218, v218, v176
	v_max_f32_e32 v219, v219, v177
	s_mov_b64 s[58:59], exec
	s_mov_b64 exec, 15
	ds_write_b128 v172, v[216:219]
	s_mov_b64 exec, s[58:59]
	s_waitcnt lgkmcnt(0)
	s_barrier
	ds_read_b128 v[140:143], v173 offset:0
	ds_read_b128 v[144:147], v173 offset:64
	ds_read_b128 v[148:151], v173 offset:128
	ds_read_b128 v[152:155], v173 offset:192
	ds_read_b128 v[156:159], v173 offset:256
	ds_read_b128 v[160:163], v173 offset:320
	ds_read_b128 v[164:167], v173 offset:384
	ds_read_b128 v[232:235], v173 offset:448
	s_waitcnt lgkmcnt(0)
	v_max3_f32 v220, v140, v144, v148
	v_max3_f32 v220, v220, v152, v156
	v_max3_f32 v220, v220, v160, v164
	v_max_f32_e32 v220, v220, v232
	v_max3_f32 v221, v141, v145, v149
	v_max3_f32 v221, v221, v153, v157
	v_max3_f32 v221, v221, v161, v165
	v_max_f32_e32 v221, v221, v233
	v_max3_f32 v222, v142, v146, v150
	v_max3_f32 v222, v222, v154, v158
	v_max3_f32 v222, v222, v162, v166
	v_max_f32_e32 v222, v222, v234
	v_max3_f32 v223, v143, v147, v151
	v_max3_f32 v223, v223, v155, v159
	v_max3_f32 v223, v223, v163, v167
	v_max_f32_e32 v223, v223, v235
	s_cmp_lg_u32 s1, 0
	s_cbranch_scc1 .Lc16p3_ffn2_nocm
	s_lshl_b32 s3, s2, 2
	s_add_u32 s54, s34, s3
	s_addc_u32 s55, s35, 0
	s_add_u32 s54, s54, 0x60000
	s_addc_u32 s55, s55, 0
	s_mov_b64 s[58:59], exec
	s_mov_b64 exec, 15
	global_store_dwordx4 v230, v[220:223], s[54:55]
	s_mov_b64 exec, s[58:59]
